# raw-tile LDS slot addresses hoisted out of the 2a item loop (4 persistent VGPRs; block-inverse temps moved to block-local registers)
# speedup vs baseline: 1.0062x; 1.0062x over previous
.LBB0_293:
	s_or_b64 exec, exec, s[4:5]
	v_and_b32_e32 v26, 64, v0
	s_and_b64 s[0:1], s[0:1], exec
	v_cmp_eq_u32_e32 vcc, 0, v26
	v_mov_b32_e32 v26, s69
	v_mov_b32_e32 v27, s67
	v_cndmask_b32_e32 v27, v26, v27, vcc
	v_mov_b32_e32 v26, s68
	v_mov_b32_e32 v28, s66
	s_movk_i32 s0, 0x100
	v_cndmask_b32_e32 v26, v26, v28, vcc
	v_cmp_gt_u32_e64 s[2:3], s0, v0
	v_mov_b32_e32 v28, 0x880
	v_mov_b32_e32 v46, 0x800
	v_lshrrev_b32_e32 v170, 1, v0
	v_and_b32_e32 v1, 63, v0
	v_writelane_b32 v250, s2, 21
	s_cselect_b32 s72, 17, 15
	s_add_u32 s88, s96, 0x2000000
	v_cndmask_b32_e64 v28, v28, v46, s[2:3]
	v_and_b32_e32 v46, 64, v170
	v_or3_b32 v28, v28, v46, v1
	v_lshlrev_b32_e32 v28, 2, v28
	v_lshl_add_u64 v[26:27], v[26:27], 0, v[28:29]
	global_load_dword v26, v[26:27], off
	s_addc_u32 s89, s97, 0
	s_add_i32 s0, 0, 0x24000
	s_lshl_b32 s55, s50, 4
	s_cmpk_gt_u32 s51, 0xff
	s_cselect_b64 s[4:5], -1, 0
	s_cmpk_lt_u32 s51, 0x100
	s_cselect_b64 vcc, -1, 0
	v_writelane_b32 v250, s3, 22
	s_and_b64 s[2:3], vcc, exec
	s_cselect_b32 s3, s45, s47
	s_cselect_b32 s2, s44, s46
	v_and_b32_e32 v110, 48, v0
	v_mov_b32_e32 v111, v29
	v_lshl_add_u32 v27, v0, 2, s0
	v_lshl_add_u64 v[112:113], s[2:3], 0, v[110:111]
	s_movk_i32 s2, 0x340
	v_cmp_gt_u32_e64 s[2:3], s2, v0
	v_bfe_u32 v171, v0, 4, 2
	s_mov_b32 s23, 0x1dc00
	v_writelane_b32 v250, s2, 23
	v_and_b32_e32 v166, 15, v0
	v_lshlrev_b32_e32 v173, 2, v171
	v_writelane_b32 v250, s3, 24
	s_mov_b32 s3, 0xd000
	s_cselect_b32 s2, 0, 0x4000
	s_cselect_b32 s22, s3, 0xf800
	v_or_b32_e32 v54, 16, v166
	v_or_b32_e32 v51, 32, v166
	v_bitop3_b32 v28, s50, v171, 3 bitop3:0x6c
	s_movk_i32 s73, 0xa0
	v_or_b32_e32 v49, 48, v1
	v_lshlrev_b32_e32 v48, 6, v28
	v_lshlrev_b32_e32 v28, 2, v166
	v_mul_u32_u24_e32 v46, 0xa0, v49
	v_lshlrev_b32_e32 v188, 2, v1
	v_and_b32_e32 v72, 4, v173
	v_lshrrev_b32_e32 v111, 3, v0
	v_or_b32_e32 v184, s55, v166
	v_mul_lo_u32 v185, v184, s73
	v_lshlrev_b32_e32 v172, 3, v171
	v_lshlrev_b32_e32 v61, 1, v166
	v_lshl_add_u32 v63, v166, 6, 0
	s_mov_b32 s1, 0
	v_and_or_b32 v176, s55, 48, v166
	v_or_b32_e32 v177, 0x200, v0
	v_or_b32_e32 v178, 0x400, v0
	v_or_b32_e32 v179, 0x600, v0
	v_mul_u32_u24_e32 v167, 0xa0, v166
	v_add_u32_e32 v205, 0x24800, v175
	v_lshrrev_b32_e32 v187, 6, v0
	v_add_u32_e32 v215, v63, v110
	v_mov_b32_e32 v220, 0x90
	v_mov_b32_e32 v138, 0
	s_waitcnt vmcnt(0)
	ds_write_b32 v27, v26
	v_and_b32_e32 v27, 7, v0
	v_lshl_add_u32 v180, v27, 5, s0
	s_mov_b32 s0, 0x8000
	s_cselect_b32 s0, s0, 0xa800
	s_add_i32 s0, s0, 0
	v_add_u32_e32 v181, s0, v110
	s_add_i32 s0, s2, 0
	v_lshl_add_u32 v47, v171, 10, s0
	s_lshl_b32 s0, s50, 8
	s_lshl_b32 s92, s50, 1
	s_add_i32 s0, s0, 0
	s_cmp_lt_u32 s51, 64
	s_cselect_b64 s[8:9], -1, 0
	s_cmpk_gt_u32 s51, 0x7f
	s_cselect_b64 s[10:11], -1, 0
	s_cmpk_gt_u32 s51, 0xbf
	s_cselect_b64 s[12:13], -1, 0
	s_cmpk_gt_u32 s51, 0x13f
	s_cselect_b64 s[14:15], -1, 0
	s_cmpk_gt_u32 s51, 0x17f
	s_cselect_b64 s[16:17], -1, 0
	s_cmpk_gt_u32 s51, 0x1bf
	s_cselect_b64 s[18:19], -1, 0
	s_cmpk_gt_u32 s51, 0x1ff
	v_writelane_b32 v250, s0, 25
	s_cselect_b64 s[20:21], -1, 0
	s_lshr_b32 s0, s51, 7
	s_cmp_eq_u32 s0, 2
	s_cselect_b64 s[2:3], -1, 0
	s_and_b64 s[6:7], s[2:3], exec
	s_cselect_b32 s6, s23, 0x20400
	s_cmp_lg_u32 s0, 1
	s_cselect_b32 s23, s6, 0x4000
	s_cmpk_lt_u32 s51, 0x80
	s_cselect_b64 s[24:25], -1, 0
	s_and_b64 s[6:7], s[24:25], exec
	s_cselect_b32 s6, 0, s23
	v_writelane_b32 v250, s24, 26
	s_or_b64 s[2:3], s[24:25], s[2:3]
	s_mov_b32 s7, 0x14800
	s_and_b64 s[2:3], s[2:3], exec
	s_cselect_b32 s7, s7, 0x12000
	s_bfe_u32 s54, s51, 0x10006
	s_bitcmp1_b32 s51, 6
	s_cselect_b64 s[2:3], -1, 0
	s_add_i32 s22, s22, 0
	v_writelane_b32 v250, s25, 27
	v_mov_b32_e32 v53, s22
	v_cmp_lt_u32_e64 s[22:23], v173, v166
	v_cmp_le_u32_e64 s[24:25], v173, v166
	s_add_i32 s7, s7, 0
	v_cndmask_b32_e64 v56, 0, 1, s[22:23]
	v_cndmask_b32_e64 v57, 0, 1, s[24:25]
	v_cndmask_b32_e32 v56, v57, v56, vcc
	v_and_b32_e32 v56, 1, v56
	v_cmp_eq_u32_e64 s[22:23], 1, v56
	v_or_b32_e32 v56, 17, v173
	v_cmp_lt_u32_e64 s[24:25], v56, v54
	v_cmp_le_u32_e64 s[26:27], v56, v54
	s_add_i32 s6, s6, 0
	v_cndmask_b32_e64 v56, 0, 1, s[24:25]
	v_cndmask_b32_e64 v57, 0, 1, s[26:27]
	v_cndmask_b32_e32 v56, v57, v56, vcc
	v_and_b32_e32 v56, 1, v56
	v_mov_b32_e32 v52, s7
	v_mov_b32_e32 v55, s6
	v_cmp_eq_u32_e64 s[6:7], 1, v56
	v_or_b32_e32 v56, 18, v173
	v_cmp_lt_u32_e64 s[26:27], v56, v54
	v_cmp_le_u32_e64 s[28:29], v56, v54
	v_writelane_b32 v250, s6, 28
	v_cndmask_b32_e64 v56, 0, 1, s[26:27]
	v_cndmask_b32_e64 v57, 0, 1, s[28:29]
	v_cndmask_b32_e32 v56, v57, v56, vcc
	v_and_b32_e32 v56, 1, v56
	v_writelane_b32 v250, s7, 29
	v_cmp_eq_u32_e64 s[6:7], 1, v56
	v_or_b32_e32 v56, 19, v173
	v_cmp_lt_u32_e64 s[28:29], v56, v54
	v_cmp_le_u32_e64 s[30:31], v56, v54
	v_writelane_b32 v250, s6, 30
	v_cndmask_b32_e64 v54, 0, 1, s[28:29]
	v_cndmask_b32_e64 v56, 0, 1, s[30:31]
	v_cndmask_b32_e32 v54, v56, v54, vcc
	v_and_b32_e32 v54, 1, v54
	v_writelane_b32 v250, s7, 31
	v_cmp_eq_u32_e64 s[6:7], 1, v54
	v_or_b32_e32 v54, 33, v173
	v_cmp_lt_u32_e64 s[30:31], v54, v51
	v_cmp_le_u32_e64 s[34:35], v54, v51
	v_writelane_b32 v250, s6, 32
	v_cndmask_b32_e64 v54, 0, 1, s[30:31]
	v_cndmask_b32_e64 v57, 0, 1, s[34:35]
	v_cndmask_b32_e32 v54, v57, v54, vcc
	v_and_b32_e32 v54, 1, v54
	v_writelane_b32 v250, s7, 33
	v_cmp_eq_u32_e64 s[6:7], 1, v54
	v_or_b32_e32 v54, 34, v173
	v_cmp_lt_u32_e64 s[34:35], v54, v51
	v_cmp_le_u32_e64 s[36:37], v54, v51
	v_writelane_b32 v250, s6, 34
	v_cndmask_b32_e64 v54, 0, 1, s[34:35]
	v_cndmask_b32_e64 v57, 0, 1, s[36:37]
	v_cndmask_b32_e32 v54, v57, v54, vcc
	v_and_b32_e32 v54, 1, v54
	v_writelane_b32 v250, s7, 35
	v_cmp_eq_u32_e64 s[6:7], 1, v54
	v_or_b32_e32 v54, 35, v173
	v_cmp_lt_u32_e64 s[36:37], v54, v51
	v_cmp_le_u32_e64 s[38:39], v54, v51
	v_writelane_b32 v250, s6, 36
	v_cndmask_b32_e64 v51, 0, 1, s[36:37]
	v_cndmask_b32_e64 v54, 0, 1, s[38:39]
	v_cndmask_b32_e32 v51, v54, v51, vcc
	v_and_b32_e32 v51, 1, v51
	v_add3_u32 v182, v47, v48, v28
	v_mad_u32_u24 v47, v166, s73, v52
	v_mad_u32_u24 v48, v166, s73, v53
	v_writelane_b32 v250, s7, 37
	v_cmp_eq_u32_e64 s[6:7], 1, v51
	v_mad_u32_u24 v51, v49, s73, v53
	v_mad_u32_u24 v53, v49, s73, v52
	v_cndmask_b32_e64 v52, 0, 1, vcc
	v_writelane_b32 v250, s6, 38
	v_or_b32_e32 v52, v173, v52
	v_mad_u32_u24 v183, v166, s73, v55
	v_writelane_b32 v250, s7, 39
	v_cmp_gt_u32_e64 s[6:7], v166, v52
	v_or_b32_e32 v52, 2, v173
	v_cmp_lt_u32_e64 s[40:41], v52, v166
	v_cmp_le_u32_e64 s[42:43], v52, v166
	v_writelane_b32 v250, s6, 40
	v_cndmask_b32_e64 v52, 0, 1, s[40:41]
	v_cndmask_b32_e64 v54, 0, 1, s[42:43]
	v_cndmask_b32_e32 v52, v54, v52, vcc
	v_and_b32_e32 v52, 1, v52
	v_writelane_b32 v250, s7, 41
	v_cmp_eq_u32_e64 s[6:7], 1, v52
	v_or_b32_e32 v52, 3, v173
	v_cmp_lt_u32_e64 s[42:43], v52, v166
	v_cmp_le_u32_e64 s[44:45], v52, v166
	v_writelane_b32 v250, s6, 42
	v_cndmask_b32_e64 v52, 0, 1, s[42:43]
	v_cndmask_b32_e64 v54, 0, 1, s[44:45]
	v_cndmask_b32_e32 v52, v54, v52, vcc
	v_and_b32_e32 v52, 1, v52
	v_writelane_b32 v250, s7, 43
	v_cmp_eq_u32_e64 s[6:7], 1, v52
	v_or_b32_e32 v52, 48, v173
	v_cmp_lt_u32_e64 s[44:45], v52, v49
	v_cmp_le_u32_e64 s[46:47], v52, v49
	v_mad_u32_u24 v189, v49, s73, v55
	v_cndmask_b32_e64 v54, 0, 1, s[44:45]
	v_cndmask_b32_e64 v55, 0, 1, s[46:47]
	v_cndmask_b32_e32 v54, v55, v54, vcc
	v_writelane_b32 v250, s6, 44
	v_and_b32_e32 v54, 1, v54
	s_mov_b32 s25, s50
	v_writelane_b32 v250, s7, 45
	v_cmp_eq_u32_e64 s[6:7], 1, v54
	v_or_b32_e32 v54, 49, v173
	v_cmp_lt_u32_e64 s[46:47], v54, v49
	v_cmp_le_u32_e64 s[48:49], v54, v49
	v_writelane_b32 v250, s6, 46
	v_cndmask_b32_e64 v54, 0, 1, s[46:47]
	v_cndmask_b32_e64 v55, 0, 1, s[48:49]
	v_cndmask_b32_e32 v54, v55, v54, vcc
	v_and_b32_e32 v54, 1, v54
	v_writelane_b32 v250, s7, 47
	v_cmp_eq_u32_e64 s[6:7], 1, v54
	v_or_b32_e32 v54, 50, v173
	v_cmp_lt_u32_e64 s[48:49], v54, v49
	s_mov_b32 s24, s51
	v_cmp_le_u32_e64 s[50:51], v54, v49
	v_cndmask_b32_e64 v54, 0, 1, s[48:49]
	v_writelane_b32 v250, s6, 48
	v_cndmask_b32_e64 v55, 0, 1, s[50:51]
	v_cndmask_b32_e32 v54, v55, v54, vcc
	v_and_b32_e32 v54, 1, v54
	v_writelane_b32 v250, s7, 49
	v_cmp_eq_u32_e64 s[6:7], 1, v54
	v_or_b32_e32 v54, 51, v173
	v_cmp_lt_u32_e64 s[50:51], v54, v49
	v_cmp_le_u32_e64 s[52:53], v54, v49
	v_writelane_b32 v250, s6, 50
	v_cndmask_b32_e64 v49, 0, 1, s[50:51]
	v_cndmask_b32_e64 v54, 0, 1, s[52:53]
	v_cndmask_b32_e32 v49, v54, v49, vcc
	v_and_b32_e32 v49, 1, v49
	v_writelane_b32 v250, s7, 51
	v_cmp_eq_u32_e64 s[6:7], 1, v49
	v_lshlrev_b32_e32 v49, 1, v52
	v_add_u32_e32 v57, 0, v28
	v_writelane_b32 v250, s6, 52
	v_lshl_or_b32 v52, s54, 5, v166
	v_mul_u32_u24_e32 v58, 0x90, v52
	v_writelane_b32 v250, s7, 53
	s_movk_i32 s7, 0x9c
	v_or_b32_e32 v52, 16, v52
	v_mad_u32_u24 v60, v166, s7, v57
	s_movk_i32 s7, 0x480
	v_mul_u32_u24_e32 v59, 0x90, v52
	v_mad_u32_u24 v52, v171, s7, 0
	s_and_b32 s7, s24, 0xffffffc0
	s_lshl_b32 s26, s0, 4
	v_add3_u32 v191, v52, s7, v28
	v_lshlrev_b32_e32 v28, 9, v171
	v_or_b32_e32 v168, s26, v166
	s_movk_i32 s6, 0x90
	v_writelane_b32 v250, s24, 54
	v_sub_u32_e32 v28, v52, v28
	v_lshl_add_u32 v62, s25, 5, v28
	v_writelane_b32 v250, s55, 55
	v_mul_lo_u32 v28, v168, s6
	s_add_i32 s6, 0, 0x20400
	s_add_i32 s93, 0, 0x1b800
	s_add_i32 s40, 0, 0x12000
	s_and_b32 s7, s92, 2
	s_add_i32 s24, 0, 0x1dc00
	v_add_u32_e32 v193, s6, v110
	s_add_i32 s6, s26, 64
	s_add_i32 s41, 0, 0x19400
	s_add_i32 s42, 0, 0x17000
	v_writelane_b32 v250, s25, 56
	s_bitcmp1_b32 s25, 0
	v_writelane_b32 v250, s26, 57
	v_or_b32_e32 v73, s26, v173
	s_movk_i32 s43, 0x120
	v_add_u32_e32 v66, s93, v28
	v_or_b32_e32 v52, s6, v166
	v_add_u32_e32 v68, s42, v28
	v_add_u32_e32 v69, s41, v28
	v_lshl_or_b32 v70, s7, 4, v166
	s_cselect_b64 s[62:63], -1, 0
	s_lshl_b32 s6, s7, 10
	v_lshl_or_b32 v169, s0, 8, v188
	s_or_b32 s0, s7, 1
	v_mul_lo_u32 v28, v73, s43
	v_writelane_b32 v250, s54, 58
	s_lshl_b32 s7, s54, 7
	v_add_u32_e32 v192, s24, v110
	s_add_i32 s24, 0, 0x22c00
	v_lshl_or_b32 v71, s0, 4, v166
	s_lshl_b32 s0, s0, 10
	v_add3_u32 v202, v57, v28, s7
	v_lshlrev_b32_e32 v28, 1, v73
	s_mov_b32 s7, 0x1ffffff0
	v_readlane_b32 s26, v250, 19
	v_and_or_b32 v57, v28, s7, v166
	v_readlane_b32 s27, v250, 20
	s_add_u32 s38, s66, 0x1000
	v_add_u32_e32 v203, 0, v28
	v_lshl_add_u64 v[118:119], s[26:27], 0, v[28:29]
	v_lshlrev_b32_e32 v28, 3, v57
	s_addc_u32 s39, s67, 0
	v_add_u32_e32 v114, s6, v169
	v_add_u32_e32 v57, s6, v28
	s_add_u32 s6, s68, 0x800
	s_addc_u32 s7, s69, 0
	v_or_b32_e32 v120, v57, v72
	v_or_b32_e32 v57, 1, v73
	v_cmp_eq_u32_e64 s[52:53], v73, v70
	v_add_u32_e32 v28, s0, v28
	v_writelane_b32 v250, s6, 59
	v_cmp_eq_u32_e32 vcc, v57, v70
	v_cndmask_b32_e64 v122, 0, 1.0, s[52:53]
	v_or_b32_e32 v124, v28, v72
	v_cmp_eq_u32_e64 s[52:53], v73, v71
	v_or_b32_e32 v28, 3, v73
	v_writelane_b32 v250, s7, 60
	s_add_u32 s6, s66, 0x800
	v_cndmask_b32_e64 v123, 0, 1.0, vcc
	v_cmp_eq_u32_e32 vcc, v57, v71
	v_cndmask_b32_e64 v126, 0, 1.0, s[52:53]
	v_or_b32_e32 v57, 2, v73
	v_cmp_eq_u32_e64 s[52:53], v28, v70
	s_addc_u32 s7, s67, 0
	v_mad_u32_u24 v26, v111, s73, 0
	v_lshlrev_b32_e32 v27, 4, v27
	v_mul_lo_u32 v186, v168, s73
	v_mul_lo_u32 v52, v52, s73
	v_cndmask_b32_e64 v127, 0, 1.0, vcc
	v_cmp_eq_u32_e32 vcc, v57, v70
	v_cndmask_b32_e64 v129, 0, 1.0, s[52:53]
	v_cmp_eq_u32_e64 s[52:53], v28, v71
	v_writelane_b32 v250, s6, 61
	v_lshlrev_b32_e32 v28, 5, v0
	v_add_u32_e32 v50, 0xa00, v183
	v_add_u32_e32 v56, 0x1400, v183
	v_add_u32_e32 v55, 0, v186
	v_add_u32_e32 v190, s93, v110
	v_add_u32_e32 v64, s40, v185
	v_add_u32_e32 v65, s40, v186
	v_add_u32_e32 v67, s40, v52
	v_lshlrev_b32_e32 v52, 6, v70
	v_lshlrev_b32_e32 v54, 6, v71
	v_add_u32_e32 v116, s0, v169
	v_cndmask_b32_e64 v128, 0, 1.0, vcc
	v_cmp_eq_u32_e32 vcc, v57, v71
	v_writelane_b32 v250, s7, 62
	s_add_u32 s6, s68, 0x1000
	v_and_b32_e32 v28, 0x3800, v28
	v_add_u32_e32 v206, v26, v27
	v_add_u32_e32 v207, v181, v46
	v_mbcnt_lo_u32_b32 v26, -1, 0
	v_mov_b32_e32 v46, 0
	v_add_u32_e32 v194, s41, v110
	v_add_u32_e32 v195, s40, v110
	v_mul_u32_u24_e32 v196, 0xa0, v70
	v_mul_u32_u24_e32 v197, 0x90, v70
	v_lshl_add_u32 v198, v70, 2, s24
	v_ashrrev_i32_e32 v115, 31, v114
	v_mul_u32_u24_e32 v199, 0xa0, v71
	v_mul_u32_u24_e32 v200, 0x90, v71
	v_lshl_add_u32 v201, v71, 2, s24
	v_ashrrev_i32_e32 v117, 31, v116
	v_lshl_add_u32 v204, v73, 2, s24
	v_ashrrev_i32_e32 v121, 31, v120
	v_ashrrev_i32_e32 v125, 31, v124
	v_cndmask_b32_e64 v131, 0, 1.0, s[52:53]
	v_cndmask_b32_e64 v130, 0, 1.0, vcc
	s_addc_u32 s7, s69, 0
	v_lshl_add_u64 v[132:133], s[70:71], 0, v[28:29]
	s_mov_b32 s34, -1
	s_movk_i32 s71, 0x630
	s_mov_b32 s44, 0x3e0f83e1
	s_movk_i32 s45, 0xfdf0
	s_movk_i32 s46, 0x2940
	s_mov_b32 s47, 0x5040100
	s_mov_b32 s70, 0xbf60033a
	v_mbcnt_hi_u32_b32 v208, -1, v26
	s_add_i32 s48, 0, 0x12280
	s_movk_i32 s49, 0x2600
	v_add_u32_e32 v209, v50, v172
	v_add_u32_e32 v210, v51, v110
	v_add_u32_e32 v211, v53, v110
	v_add_u32_e32 v212, v189, v49
	v_add_u32_e32 v213, v60, v172
	v_add_u32_e32 v214, v62, v61
	v_add_u32_e32 v216, v64, v172
	v_add_u32_e32 v217, v65, v110
	v_lshlrev_b32_e32 v134, 1, v52
	v_add_u32_e32 v218, v68, v110
	v_add_u32_e32 v219, v69, v110
	v_lshlrev_b32_e32 v136, 1, v54
	v_add_u32_e32 v221, v47, v110
	v_add_u32_e32 v222, v48, v110
	v_add_u32_e32 v223, v56, v172
	v_mov_b32_e32 v139, v46
	v_add_u32_e32 v224, v55, v110
	v_add_u32_e32 v225, v190, v58
	v_add_u32_e32 v226, v190, v59
	v_add_u32_e32 v227, v66, v110
	v_add_u32_e32 v228, v67, v110
	s_mov_b32 s51, 0
	v_lshrrev_b32_e32 v26, 3, v0
	v_and_b32_e32 v27, 7, v0
	v_mul_u32_u24_e32 v26, 0x2600, v26
	v_lshl_add_u32 v251, v27, 4, v26
	v_mov_b32_e32 v26, v0
	v_lshrrev_b32_e32 v27, 4, v26
	v_mul_u32_u24_e32 v27, 0x7c2, v27
	v_lshrrev_b32_e32 v27, 16, v27
	v_mul_u32_u24_e32 v28, 0x210, v27
	v_sub_u32_e32 v26, v26, v28
	v_lshrrev_b32_e32 v28, 3, v26
	v_and_b32_e32 v26, 7, v26
	v_mul_u32_u24_e32 v28, 0x2600, v28
	v_lshl_add_u32 v28, v27, 10, v28
	v_lshl_add_u32 v252, v26, 4, v28
	v_add_u32_e32 v26, 0x200, v0
	v_lshrrev_b32_e32 v27, 4, v26
	v_mul_u32_u24_e32 v27, 0x7c2, v27
	v_lshrrev_b32_e32 v27, 16, v27
	v_mul_u32_u24_e32 v28, 0x210, v27
	v_sub_u32_e32 v26, v26, v28
	v_lshrrev_b32_e32 v28, 3, v26
	v_and_b32_e32 v26, 7, v26
	v_mul_u32_u24_e32 v28, 0x2600, v28
	v_lshl_add_u32 v28, v27, 10, v28
	v_lshl_add_u32 v253, v26, 4, v28
	v_add_u32_e32 v26, 0x400, v0
	v_lshrrev_b32_e32 v27, 4, v26
	v_mul_u32_u24_e32 v27, 0x7c2, v27
	v_lshrrev_b32_e32 v27, 16, v27
	v_mul_u32_u24_e32 v28, 0x210, v27
	v_sub_u32_e32 v26, v26, v28
	v_lshrrev_b32_e32 v28, 3, v26
	v_and_b32_e32 v26, 7, v26
	v_mul_u32_u24_e32 v28, 0x2600, v28
	v_lshl_add_u32 v28, v27, 10, v28
	v_lshl_add_u32 v254, v26, 4, v28
	v_add_u32_e32 v26, 0x600, v0
	v_lshrrev_b32_e32 v27, 4, v26
	v_mul_u32_u24_e32 v27, 0x7c2, v27
	v_lshrrev_b32_e32 v27, 16, v27
	v_mul_u32_u24_e32 v28, 0x210, v27
	v_sub_u32_e32 v26, v26, v28
	v_lshrrev_b32_e32 v28, 3, v26
	v_and_b32_e32 v26, 7, v26
	v_mul_u32_u24_e32 v28, 0x2600, v28
	v_lshl_add_u32 v28, v27, 10, v28
	v_lshl_add_u32 v255, v26, 4, v28
	v_mov_b32_e32 v26, v0
	v_cmp_lt_u32_e32 vcc, 0x20f, v26
	s_nop 1
	v_cndmask_b32_e64 v27, 0, 1, vcc
	v_cmp_lt_u32_e32 vcc, 0x41f, v26
	s_nop 1
	v_addc_co_u32_e32 v27, vcc, 0, v27, vcc
	v_mul_u32_u24_e32 v28, 0x210, v27
	v_sub_u32_e32 v28, v26, v28
	v_lshrrev_b32_e32 v28, 3, v28
	v_mul_u32_u24_e32 v28, 0xa0, v28
	v_mul_u32_u24_e32 v27, 0x2940, v27
	v_and_b32_e32 v26, 7, v26
	v_lshlrev_b32_e32 v26, 4, v26
	v_add3_u32 v110, v27, v28, v26
	v_add_u32_e32 v26, 0x200, v0
	v_cmp_lt_u32_e32 vcc, 0x20f, v26
	s_nop 1
	v_cndmask_b32_e64 v27, 0, 1, vcc
	v_cmp_lt_u32_e32 vcc, 0x41f, v26
	s_nop 1
	v_addc_co_u32_e32 v27, vcc, 0, v27, vcc
	v_mul_u32_u24_e32 v28, 0x210, v27
	v_sub_u32_e32 v28, v26, v28
	v_lshrrev_b32_e32 v28, 3, v28
	v_mul_u32_u24_e32 v28, 0xa0, v28
	v_mul_u32_u24_e32 v27, 0x2940, v27
	v_and_b32_e32 v26, 7, v26
	v_lshlrev_b32_e32 v26, 4, v26
	v_add3_u32 v111, v27, v28, v26
	v_add_u32_e32 v26, 0x400, v0
	v_cmp_lt_u32_e32 vcc, 0x20f, v26
	s_nop 1
	v_cndmask_b32_e64 v27, 0, 1, vcc
	v_cmp_lt_u32_e32 vcc, 0x41f, v26
	s_nop 1
	v_addc_co_u32_e32 v27, vcc, 0, v27, vcc
	v_mul_u32_u24_e32 v28, 0x210, v27
	v_sub_u32_e32 v28, v26, v28
	v_lshrrev_b32_e32 v28, 3, v28
	v_mul_u32_u24_e32 v28, 0xa0, v28
	v_mul_u32_u24_e32 v27, 0x2940, v27
	v_and_b32_e32 v26, 7, v26
	v_lshlrev_b32_e32 v26, 4, v26
	v_add3_u32 v166, v27, v28, v26
	v_add_u32_e32 v26, 0x600, v0
	v_cmp_lt_u32_e32 vcc, 0x20f, v26
	s_nop 1
	v_cndmask_b32_e64 v27, 0, 1, vcc
	v_cmp_lt_u32_e32 vcc, 0x41f, v26
	s_nop 1
	v_addc_co_u32_e32 v27, vcc, 0, v27, vcc
	v_mul_u32_u24_e32 v28, 0x210, v27
	v_sub_u32_e32 v28, v26, v28
	v_lshrrev_b32_e32 v28, 3, v28
	v_mul_u32_u24_e32 v28, 0xa0, v28
	v_mul_u32_u24_e32 v27, 0x2940, v27
	v_and_b32_e32 v26, 7, v26
	v_lshlrev_b32_e32 v26, 4, v26
	v_add3_u32 v168, v27, v28, v26
	s_branch .LBB0_295

.LBB0_332:
	s_waitcnt vmcnt(8)
	ds_write_b128 v110, v[30:33] offset:53248
	ds_write_b128 v111, v[34:37] offset:53248
	ds_write_b128 v166, v[38:41] offset:53248
	v_cmp_gt_i32_e32 vcc, s71, v179
	s_and_saveexec_b64 s[24:25], vcc
	s_cbranch_execz .LBB0_340
	ds_write_b128 v168, v[42:45] offset:53248

.Lp5_skip:
	v_readfirstlane_b32 s26, v0
	s_lshr_b32 s26, s26, 6
	s_cmp_gt_u32 s26, 3
	s_cbranch_scc1 .LBB0_391
	s_mul_i32 s27, s26, 0xa20
	v_and_b32_e32 v28, 63, v0
	v_and_b32_e32 v86, 15, v28
	v_lshrrev_b32_e32 v87, 4, v28
	v_mul_u32_u24_e32 v88, 0xa0, v86
	v_lshl_add_u32 v88, v87, 3, v88
	v_add_u32_e32 v88, s27, v88
	ds_read_b64 v[26:27], v88
	v_lshrrev_b32_e32 v89, 2, v86
	v_lshl_add_u32 v89, v87, 2, v89
	v_mul_u32_u24_e32 v89, 0xa0, v89
	v_and_b32_e32 v28, 3, v86
	v_lshl_add_u32 v89, v28, 3, v89
	v_add_u32_e32 v89, s27, v89
	ds_read_b64_tr_b16 v[78:79], v89
	s_lshl_b32 s27, s26, 10
	v_lshlrev_b32_e32 v88, 6, v86
	v_lshl_add_u32 v88, v87, 4, v88
	v_add_u32_e32 v88, s27, v88
	v_add_u32_e32 v88, 0x2800, v88
	v_lshlrev_b32_e32 v28, 2, v87
	v_sub_u32_e32 v28, v86, v28
	v_med3_i32 v66, v28, 0, 4
	v_lshlrev_b32_e64 v66, v66, 1
	v_add_u32_e32 v66, -1, v66
	v_lshlrev_b32_e64 v67, v28, 1
	v_and_b32_e32 v67, 15, v67
	v_bfe_i32 v72, v66, 0, 1
	v_bfe_i32 v73, v66, 1, 1
	v_lshrrev_b32_e32 v72, 16, v72
	v_and_b32_e32 v73, 0xffff0000, v73
	v_or_b32_e32 v68, v72, v73
	v_bfe_i32 v72, v66, 2, 1
	v_bfe_i32 v73, v66, 3, 1
	v_lshrrev_b32_e32 v72, 16, v72
	v_and_b32_e32 v73, 0xffff0000, v73
	v_or_b32_e32 v69, v72, v73
	v_bfe_i32 v72, v67, 0, 1
	v_bfe_i32 v73, v67, 1, 1
	v_lshrrev_b32_e32 v72, 16, v72
	v_and_b32_e32 v73, 0xffff0000, v73
	v_or_b32_e32 v70, v72, v73
	v_bfe_i32 v72, v67, 2, 1
	v_bfe_i32 v73, v67, 3, 1
	v_lshrrev_b32_e32 v72, 16, v72
	v_and_b32_e32 v73, 0xffff0000, v73
	v_or_b32_e32 v71, v72, v73
	v_or_b32_e32 v74, v68, v70
	v_or_b32_e32 v75, v69, v71
	v_not_b32_e32 v74, v74
	v_not_b32_e32 v75, v75
	v_and_b32_e32 v86, 0x3f803f80, v70
	v_and_b32_e32 v87, 0x3f803f80, v71
	v_and_b32_e32 v76, 0x80008000, v68
	v_and_b32_e32 v77, 0x80008000, v69
	s_waitcnt lgkmcnt(1)
	v_and_b32_e32 v26, v26, v68
	v_and_b32_e32 v27, v27, v69
	s_waitcnt lgkmcnt(0)
	v_and_b32_e32 v78, v78, v74
	v_and_b32_e32 v79, v79, v75
	v_xor_b32_e32 v80, v26, v76
	v_xor_b32_e32 v81, v27, v77
	v_or_b32_e32 v80, v80, v86
	v_or_b32_e32 v81, v81, v87
	v_mfma_f32_16x16x16_bf16 v[66:69], v[26:27], v[78:79], 0
	v_mfma_f32_16x16x16_bf16 v[70:73], v[78:79], v[26:27], 0
	s_nop 7
	v_cvt_pk_bf16_f32 v82, v66, v67
	v_cvt_pk_bf16_f32 v83, v68, v69
	v_cvt_pk_bf16_f32 v84, v70, v71
	v_cvt_pk_bf16_f32 v85, v72, v73
	v_or_b32_e32 v26, v82, v86
	v_or_b32_e32 v27, v83, v87
	s_nop 1
	v_mfma_f32_16x16x16_bf16 v[74:77], v[26:27], v[80:81], 0
	v_mfma_f32_16x16x16_bf16 v[66:69], v[84:85], v[82:83], 0
	v_mfma_f32_16x16x16_bf16 v[70:73], v[82:83], v[84:85], 0
	s_nop 6
	v_cvt_pk_bf16_f32 v26, v74, v75
	v_cvt_pk_bf16_f32 v27, v76, v77
	v_cvt_pk_bf16_f32 v78, v66, v67
	v_cvt_pk_bf16_f32 v79, v68, v69
	v_cvt_pk_bf16_f32 v80, v70, v71
	v_cvt_pk_bf16_f32 v81, v72, v73
	s_nop 1
	v_mfma_f32_16x16x16_bf16 v[66:69], v[80:81], v[78:79], 0
	v_or_b32_e32 v80, v80, v86
	v_or_b32_e32 v81, v81, v87
	s_nop 6
	v_cvt_pk_bf16_f32 v78, v66, v67
	v_cvt_pk_bf16_f32 v79, v68, v69
	v_or_b32_e32 v78, v78, v86
	v_or_b32_e32 v79, v79, v87
	s_nop 1
	v_mfma_f32_16x16x16_bf16 v[70:73], v[80:81], v[78:79], 0
	s_nop 7
	v_cvt_pk_bf16_f32 v82, v70, v71
	v_cvt_pk_bf16_f32 v83, v72, v73
	s_nop 1
	v_mfma_f32_16x16x16_bf16 v[66:69], v[82:83], v[26:27], 0
	s_nop 7
	ds_write_b128 v88, v[66:69]
	s_branch .LBB0_391

.LBB0_463:
	s_or_b64 exec, exec, s[2:3]
	v_readlane_b32 s0, v250, 18
	v_readlane_b32 s1, v250, 3
	v_readfirstlane_b32 s2, v0
	v_and_b32_e32 v1, 63, v0
	v_and_b32_e32 v12, 15, v1
	v_lshrrev_b32_e32 v13, 4, v1
	s_lshr_b32 s2, s2, 6
	s_and_b32 s3, s2, 1
	s_lshr_b32 s4, s2, 1
	s_and_b32 s1, s1, 1
	s_ashr_i32 s0, s0, 1
	s_lshl_b32 s0, s0, 19
	s_lshr_b32 s16, s0, 6
	s_mov_b32 s17, 0
	s_lshl_b32 s5, s4, 11
	v_lshl_add_u32 v14, v1, 4, s5
	v_mov_b32_e32 v15, 0
	s_lshl_b32 s5, s4, 4
	v_add_u32_e32 v16, s5, v12
	v_lshlrev_b32_e32 v16, 6, v16
	s_lshl_b32 s5, s1, 5
	v_lshl_add_u32 v17, v13, 2, s5
	v_add_u32_e32 v16, v16, v17
	v_lshlrev_b32_e32 v16, 1, v16
	v_mov_b32_e32 v17, 0
	s_lshl_b32 s5, s1, 3
	s_add_i32 s5, s5, s4
	s_lshl_b32 s5, s5, 9
	v_lshl_add_u32 v18, v1, 3, s5
	v_mov_b32_e32 v19, 0
	s_mov_b32 s8, 0x2000
	s_mov_b32 s9, 0
	v_mul_u32_u24_e32 v10, 0xa0, v12
	s_lshl_b32 s5, s4, 5
	v_lshl_add_u32 v11, v13, 3, s5
	v_add_u32_e32 v11, v11, v10
	v_lshl_add_u32 v10, v13, 4, v10
	s_cmp_eq_u32 s3, 0
	s_cbranch_scc0 .Lsp_hrole
	s_add_u32 s6, s58, s0
	s_addc_u32 s7, s59, 0
	v_lshl_add_u64 v[2:3], s[6:7], 0, v[14:15]
	s_add_u32 s6, s48, s0
	s_addc_u32 s7, s49, 0
	v_lshl_add_u64 v[6:7], s[6:7], 0, v[16:17]
	v_lshl_add_u64 v[182:183], s[6:7], 0, v[16:17]
	global_load_dwordx4 v[20:23], v[2:3], off
	global_load_dwordx4 v[24:27], v[2:3], off offset:1024
	global_load_dwordx2 v[28:29], v[6:7], off
	global_load_dwordx2 v[30:31], v[6:7], off offset:32
	v_lshl_add_u64 v[2:3], v[2:3], 0, s[8:9]
	v_lshl_add_u64 v[6:7], v[6:7], 0, s[8:9]
	global_load_dwordx4 v[32:35], v[2:3], off
	global_load_dwordx4 v[36:39], v[2:3], off offset:1024
	global_load_dwordx2 v[40:41], v[6:7], off
	global_load_dwordx2 v[42:43], v[6:7], off offset:32
	v_lshl_add_u64 v[2:3], v[2:3], 0, s[8:9]
	v_lshl_add_u64 v[6:7], v[6:7], 0, s[8:9]
	global_load_dwordx4 v[44:47], v[2:3], off
	global_load_dwordx4 v[48:51], v[2:3], off offset:1024
	global_load_dwordx2 v[52:53], v[6:7], off
	global_load_dwordx2 v[54:55], v[6:7], off offset:32
	v_lshl_add_u64 v[2:3], v[2:3], 0, s[8:9]
	v_lshl_add_u64 v[6:7], v[6:7], 0, s[8:9]
	global_load_dwordx4 v[56:59], v[2:3], off
	global_load_dwordx4 v[60:63], v[2:3], off offset:1024
	global_load_dwordx2 v[64:65], v[6:7], off
	global_load_dwordx2 v[66:67], v[6:7], off offset:32
	v_lshl_add_u64 v[2:3], v[2:3], 0, s[8:9]
	v_lshl_add_u64 v[6:7], v[6:7], 0, s[8:9]
	global_load_dwordx4 v[68:71], v[2:3], off
	global_load_dwordx4 v[72:75], v[2:3], off offset:1024
	global_load_dwordx2 v[76:77], v[6:7], off
	global_load_dwordx2 v[78:79], v[6:7], off offset:32
	v_lshl_add_u64 v[2:3], v[2:3], 0, s[8:9]
	v_lshl_add_u64 v[6:7], v[6:7], 0, s[8:9]
	global_load_dwordx4 v[80:83], v[2:3], off
	global_load_dwordx4 v[84:87], v[2:3], off offset:1024
	global_load_dwordx2 v[88:89], v[6:7], off
	global_load_dwordx2 v[90:91], v[6:7], off offset:32
	v_lshl_add_u64 v[2:3], v[2:3], 0, s[8:9]
	v_lshl_add_u64 v[6:7], v[6:7], 0, s[8:9]
	global_load_dwordx4 v[92:95], v[2:3], off
	global_load_dwordx4 v[96:99], v[2:3], off offset:1024
	global_load_dwordx2 v[100:101], v[6:7], off
	global_load_dwordx2 v[102:103], v[6:7], off offset:32
	v_lshl_add_u64 v[2:3], v[2:3], 0, s[8:9]
	v_lshl_add_u64 v[6:7], v[6:7], 0, s[8:9]
	s_waitcnt lgkmcnt(0)
	s_barrier
	global_load_dwordx4 v[104:107], v[2:3], off
	global_load_dwordx4 v[108:111], v[2:3], off offset:1024
	global_load_dwordx2 v[112:113], v[6:7], off
	global_load_dwordx2 v[114:115], v[6:7], off offset:32
	v_lshl_add_u64 v[2:3], v[2:3], 0, s[8:9]
	v_lshl_add_u64 v[6:7], v[6:7], 0, s[8:9]
	ds_read_b128 v[184:187], v10
	ds_read_b128 v[192:195], v10 offset:2560
	ds_read_b128 v[188:191], v10 offset:64
	ds_read_b128 v[196:199], v10 offset:2624
	s_waitcnt vmcnt(28)
	v_lshlrev_b32_e32 v200, 16, v28
	v_and_b32_e32 v201, 0xffff0000, v28
	v_lshlrev_b32_e32 v202, 16, v29
	v_and_b32_e32 v203, 0xffff0000, v29
	v_lshlrev_b32_e32 v204, 16, v30
	v_and_b32_e32 v205, 0xffff0000, v30
	v_lshlrev_b32_e32 v206, 16, v31
	v_and_b32_e32 v207, 0xffff0000, v31
	s_waitcnt lgkmcnt(2)
	v_mfma_f32_16x16x32_bf16 v[200:203], v[184:187], v[20:23], v[200:203]
	v_mfma_f32_16x16x32_bf16 v[204:207], v[192:195], v[20:23], v[204:207]
	s_waitcnt lgkmcnt(0)
	v_mfma_f32_16x16x32_bf16 v[200:203], v[188:191], v[24:27], v[200:203]
	v_mfma_f32_16x16x32_bf16 v[204:207], v[196:199], v[24:27], v[204:207]
	s_nop 6
	v_cvt_pk_bf16_f32 v200, v200, v201
	v_cvt_pk_bf16_f32 v201, v202, v203
	v_cvt_pk_bf16_f32 v204, v204, v205
	v_cvt_pk_bf16_f32 v205, v206, v207
	global_store_dwordx2 v[182:183], v[200:201], off
	global_store_dwordx2 v[182:183], v[204:205], off offset:32
	v_lshl_add_u64 v[182:183], v[182:183], 0, s[8:9]
	s_waitcnt lgkmcnt(0)
	s_barrier
	global_load_dwordx4 v[20:23], v[2:3], off
	global_load_dwordx4 v[24:27], v[2:3], off offset:1024
	global_load_dwordx2 v[28:29], v[6:7], off
	global_load_dwordx2 v[30:31], v[6:7], off offset:32
	v_lshl_add_u64 v[2:3], v[2:3], 0, s[8:9]
	v_lshl_add_u64 v[6:7], v[6:7], 0, s[8:9]
	ds_read_b128 v[184:187], v10 offset:5120
	ds_read_b128 v[192:195], v10 offset:7680
	ds_read_b128 v[188:191], v10 offset:5184
	ds_read_b128 v[196:199], v10 offset:7744
	s_waitcnt vmcnt(30)
	v_lshlrev_b32_e32 v200, 16, v40
	v_and_b32_e32 v201, 0xffff0000, v40
	v_lshlrev_b32_e32 v202, 16, v41
	v_and_b32_e32 v203, 0xffff0000, v41
	v_lshlrev_b32_e32 v204, 16, v42
	v_and_b32_e32 v205, 0xffff0000, v42
	v_lshlrev_b32_e32 v206, 16, v43
	v_and_b32_e32 v207, 0xffff0000, v43
	s_waitcnt lgkmcnt(2)
	v_mfma_f32_16x16x32_bf16 v[200:203], v[184:187], v[32:35], v[200:203]
	v_mfma_f32_16x16x32_bf16 v[204:207], v[192:195], v[32:35], v[204:207]
	s_waitcnt lgkmcnt(0)
	v_mfma_f32_16x16x32_bf16 v[200:203], v[188:191], v[36:39], v[200:203]
	v_mfma_f32_16x16x32_bf16 v[204:207], v[196:199], v[36:39], v[204:207]
	s_nop 6
	v_cvt_pk_bf16_f32 v200, v200, v201
	v_cvt_pk_bf16_f32 v201, v202, v203
	v_cvt_pk_bf16_f32 v204, v204, v205
	v_cvt_pk_bf16_f32 v205, v206, v207
	global_store_dwordx2 v[182:183], v[200:201], off
	global_store_dwordx2 v[182:183], v[204:205], off offset:32
	v_lshl_add_u64 v[182:183], v[182:183], 0, s[8:9]
	s_waitcnt lgkmcnt(0)
	s_barrier
	global_load_dwordx4 v[32:35], v[2:3], off
	global_load_dwordx4 v[36:39], v[2:3], off offset:1024
	global_load_dwordx2 v[40:41], v[6:7], off
	global_load_dwordx2 v[42:43], v[6:7], off offset:32
	v_lshl_add_u64 v[2:3], v[2:3], 0, s[8:9]
	v_lshl_add_u64 v[6:7], v[6:7], 0, s[8:9]
	ds_read_b128 v[184:187], v10
	ds_read_b128 v[192:195], v10 offset:2560
	ds_read_b128 v[188:191], v10 offset:64
	ds_read_b128 v[196:199], v10 offset:2624
	s_waitcnt vmcnt(32)
	v_lshlrev_b32_e32 v200, 16, v52
	v_and_b32_e32 v201, 0xffff0000, v52
	v_lshlrev_b32_e32 v202, 16, v53
	v_and_b32_e32 v203, 0xffff0000, v53
	v_lshlrev_b32_e32 v204, 16, v54
	v_and_b32_e32 v205, 0xffff0000, v54
	v_lshlrev_b32_e32 v206, 16, v55
	v_and_b32_e32 v207, 0xffff0000, v55
	s_waitcnt lgkmcnt(2)
	v_mfma_f32_16x16x32_bf16 v[200:203], v[184:187], v[44:47], v[200:203]
	v_mfma_f32_16x16x32_bf16 v[204:207], v[192:195], v[44:47], v[204:207]
	s_waitcnt lgkmcnt(0)
	v_mfma_f32_16x16x32_bf16 v[200:203], v[188:191], v[48:51], v[200:203]
	v_mfma_f32_16x16x32_bf16 v[204:207], v[196:199], v[48:51], v[204:207]
	s_nop 6
	v_cvt_pk_bf16_f32 v200, v200, v201
	v_cvt_pk_bf16_f32 v201, v202, v203
	v_cvt_pk_bf16_f32 v204, v204, v205
	v_cvt_pk_bf16_f32 v205, v206, v207
	global_store_dwordx2 v[182:183], v[200:201], off
	global_store_dwordx2 v[182:183], v[204:205], off offset:32
	v_lshl_add_u64 v[182:183], v[182:183], 0, s[8:9]
	s_waitcnt lgkmcnt(0)
	s_barrier
	global_load_dwordx4 v[44:47], v[2:3], off
	global_load_dwordx4 v[48:51], v[2:3], off offset:1024
	global_load_dwordx2 v[52:53], v[6:7], off
	global_load_dwordx2 v[54:55], v[6:7], off offset:32
	v_lshl_add_u64 v[2:3], v[2:3], 0, s[8:9]
	v_lshl_add_u64 v[6:7], v[6:7], 0, s[8:9]
	ds_read_b128 v[184:187], v10 offset:5120
	ds_read_b128 v[192:195], v10 offset:7680
	ds_read_b128 v[188:191], v10 offset:5184
	ds_read_b128 v[196:199], v10 offset:7744
	s_waitcnt vmcnt(34)
	v_lshlrev_b32_e32 v200, 16, v64
	v_and_b32_e32 v201, 0xffff0000, v64
	v_lshlrev_b32_e32 v202, 16, v65
	v_and_b32_e32 v203, 0xffff0000, v65
	v_lshlrev_b32_e32 v204, 16, v66
	v_and_b32_e32 v205, 0xffff0000, v66
	v_lshlrev_b32_e32 v206, 16, v67
	v_and_b32_e32 v207, 0xffff0000, v67
	s_waitcnt lgkmcnt(2)
	v_mfma_f32_16x16x32_bf16 v[200:203], v[184:187], v[56:59], v[200:203]
	v_mfma_f32_16x16x32_bf16 v[204:207], v[192:195], v[56:59], v[204:207]
	s_waitcnt lgkmcnt(0)
	v_mfma_f32_16x16x32_bf16 v[200:203], v[188:191], v[60:63], v[200:203]
	v_mfma_f32_16x16x32_bf16 v[204:207], v[196:199], v[60:63], v[204:207]
	s_nop 6
	v_cvt_pk_bf16_f32 v200, v200, v201
	v_cvt_pk_bf16_f32 v201, v202, v203
	v_cvt_pk_bf16_f32 v204, v204, v205
	v_cvt_pk_bf16_f32 v205, v206, v207
	global_store_dwordx2 v[182:183], v[200:201], off
	global_store_dwordx2 v[182:183], v[204:205], off offset:32
	v_lshl_add_u64 v[182:183], v[182:183], 0, s[8:9]
	s_waitcnt lgkmcnt(0)
	s_barrier
	global_load_dwordx4 v[56:59], v[2:3], off
	global_load_dwordx4 v[60:63], v[2:3], off offset:1024
	global_load_dwordx2 v[64:65], v[6:7], off
	global_load_dwordx2 v[66:67], v[6:7], off offset:32
	v_lshl_add_u64 v[2:3], v[2:3], 0, s[8:9]
	v_lshl_add_u64 v[6:7], v[6:7], 0, s[8:9]
	ds_read_b128 v[184:187], v10
	ds_read_b128 v[192:195], v10 offset:2560
	ds_read_b128 v[188:191], v10 offset:64
	ds_read_b128 v[196:199], v10 offset:2624
	s_waitcnt vmcnt(36)
	v_lshlrev_b32_e32 v200, 16, v76
	v_and_b32_e32 v201, 0xffff0000, v76
	v_lshlrev_b32_e32 v202, 16, v77
	v_and_b32_e32 v203, 0xffff0000, v77
	v_lshlrev_b32_e32 v204, 16, v78
	v_and_b32_e32 v205, 0xffff0000, v78
	v_lshlrev_b32_e32 v206, 16, v79
	v_and_b32_e32 v207, 0xffff0000, v79
	s_waitcnt lgkmcnt(2)
	v_mfma_f32_16x16x32_bf16 v[200:203], v[184:187], v[68:71], v[200:203]
	v_mfma_f32_16x16x32_bf16 v[204:207], v[192:195], v[68:71], v[204:207]
	s_waitcnt lgkmcnt(0)
	v_mfma_f32_16x16x32_bf16 v[200:203], v[188:191], v[72:75], v[200:203]
	v_mfma_f32_16x16x32_bf16 v[204:207], v[196:199], v[72:75], v[204:207]
	s_nop 6
	v_cvt_pk_bf16_f32 v200, v200, v201
	v_cvt_pk_bf16_f32 v201, v202, v203
	v_cvt_pk_bf16_f32 v204, v204, v205
	v_cvt_pk_bf16_f32 v205, v206, v207
	global_store_dwordx2 v[182:183], v[200:201], off
	global_store_dwordx2 v[182:183], v[204:205], off offset:32
	v_lshl_add_u64 v[182:183], v[182:183], 0, s[8:9]
	s_waitcnt lgkmcnt(0)
	s_barrier
	global_load_dwordx4 v[68:71], v[2:3], off
	global_load_dwordx4 v[72:75], v[2:3], off offset:1024
	global_load_dwordx2 v[76:77], v[6:7], off
	global_load_dwordx2 v[78:79], v[6:7], off offset:32
	v_lshl_add_u64 v[2:3], v[2:3], 0, s[8:9]
	v_lshl_add_u64 v[6:7], v[6:7], 0, s[8:9]
	ds_read_b128 v[184:187], v10 offset:5120
	ds_read_b128 v[192:195], v10 offset:7680
	ds_read_b128 v[188:191], v10 offset:5184
	ds_read_b128 v[196:199], v10 offset:7744
	s_waitcnt vmcnt(38)
	v_lshlrev_b32_e32 v200, 16, v88
	v_and_b32_e32 v201, 0xffff0000, v88
	v_lshlrev_b32_e32 v202, 16, v89
	v_and_b32_e32 v203, 0xffff0000, v89
	v_lshlrev_b32_e32 v204, 16, v90
	v_and_b32_e32 v205, 0xffff0000, v90
	v_lshlrev_b32_e32 v206, 16, v91
	v_and_b32_e32 v207, 0xffff0000, v91
	s_waitcnt lgkmcnt(2)
	v_mfma_f32_16x16x32_bf16 v[200:203], v[184:187], v[80:83], v[200:203]
	v_mfma_f32_16x16x32_bf16 v[204:207], v[192:195], v[80:83], v[204:207]
	s_waitcnt lgkmcnt(0)
	v_mfma_f32_16x16x32_bf16 v[200:203], v[188:191], v[84:87], v[200:203]
	v_mfma_f32_16x16x32_bf16 v[204:207], v[196:199], v[84:87], v[204:207]
	s_nop 6
	v_cvt_pk_bf16_f32 v200, v200, v201
	v_cvt_pk_bf16_f32 v201, v202, v203
	v_cvt_pk_bf16_f32 v204, v204, v205
	v_cvt_pk_bf16_f32 v205, v206, v207
	global_store_dwordx2 v[182:183], v[200:201], off
	global_store_dwordx2 v[182:183], v[204:205], off offset:32
	v_lshl_add_u64 v[182:183], v[182:183], 0, s[8:9]
	s_waitcnt lgkmcnt(0)
	s_barrier
	global_load_dwordx4 v[80:83], v[2:3], off
	global_load_dwordx4 v[84:87], v[2:3], off offset:1024
	global_load_dwordx2 v[88:89], v[6:7], off
	global_load_dwordx2 v[90:91], v[6:7], off offset:32
	v_lshl_add_u64 v[2:3], v[2:3], 0, s[8:9]
	v_lshl_add_u64 v[6:7], v[6:7], 0, s[8:9]
	ds_read_b128 v[184:187], v10
	ds_read_b128 v[192:195], v10 offset:2560
	ds_read_b128 v[188:191], v10 offset:64
	ds_read_b128 v[196:199], v10 offset:2624
	s_waitcnt vmcnt(40)
	v_lshlrev_b32_e32 v200, 16, v100
	v_and_b32_e32 v201, 0xffff0000, v100
	v_lshlrev_b32_e32 v202, 16, v101
	v_and_b32_e32 v203, 0xffff0000, v101
	v_lshlrev_b32_e32 v204, 16, v102
	v_and_b32_e32 v205, 0xffff0000, v102
	v_lshlrev_b32_e32 v206, 16, v103
	v_and_b32_e32 v207, 0xffff0000, v103
	s_waitcnt lgkmcnt(2)
	v_mfma_f32_16x16x32_bf16 v[200:203], v[184:187], v[92:95], v[200:203]
	v_mfma_f32_16x16x32_bf16 v[204:207], v[192:195], v[92:95], v[204:207]
	s_waitcnt lgkmcnt(0)
	v_mfma_f32_16x16x32_bf16 v[200:203], v[188:191], v[96:99], v[200:203]
	v_mfma_f32_16x16x32_bf16 v[204:207], v[196:199], v[96:99], v[204:207]
	s_nop 6
	v_cvt_pk_bf16_f32 v200, v200, v201
	v_cvt_pk_bf16_f32 v201, v202, v203
	v_cvt_pk_bf16_f32 v204, v204, v205
	v_cvt_pk_bf16_f32 v205, v206, v207
	global_store_dwordx2 v[182:183], v[200:201], off
	global_store_dwordx2 v[182:183], v[204:205], off offset:32
	v_lshl_add_u64 v[182:183], v[182:183], 0, s[8:9]
	s_waitcnt lgkmcnt(0)
	s_barrier
	global_load_dwordx4 v[92:95], v[2:3], off
	global_load_dwordx4 v[96:99], v[2:3], off offset:1024
	global_load_dwordx2 v[100:101], v[6:7], off
	global_load_dwordx2 v[102:103], v[6:7], off offset:32
	v_lshl_add_u64 v[2:3], v[2:3], 0, s[8:9]
	v_lshl_add_u64 v[6:7], v[6:7], 0, s[8:9]
	ds_read_b128 v[184:187], v10 offset:5120
	ds_read_b128 v[192:195], v10 offset:7680
	ds_read_b128 v[188:191], v10 offset:5184
	ds_read_b128 v[196:199], v10 offset:7744
	s_waitcnt vmcnt(42)
	v_lshlrev_b32_e32 v200, 16, v112
	v_and_b32_e32 v201, 0xffff0000, v112
	v_lshlrev_b32_e32 v202, 16, v113
	v_and_b32_e32 v203, 0xffff0000, v113
	v_lshlrev_b32_e32 v204, 16, v114
	v_and_b32_e32 v205, 0xffff0000, v114
	v_lshlrev_b32_e32 v206, 16, v115
	v_and_b32_e32 v207, 0xffff0000, v115
	s_waitcnt lgkmcnt(2)
	v_mfma_f32_16x16x32_bf16 v[200:203], v[184:187], v[104:107], v[200:203]
	v_mfma_f32_16x16x32_bf16 v[204:207], v[192:195], v[104:107], v[204:207]
	s_waitcnt lgkmcnt(0)
	v_mfma_f32_16x16x32_bf16 v[200:203], v[188:191], v[108:111], v[200:203]
	v_mfma_f32_16x16x32_bf16 v[204:207], v[196:199], v[108:111], v[204:207]
	s_nop 6
	v_cvt_pk_bf16_f32 v200, v200, v201
	v_cvt_pk_bf16_f32 v201, v202, v203
	v_cvt_pk_bf16_f32 v204, v204, v205
	v_cvt_pk_bf16_f32 v205, v206, v207
	global_store_dwordx2 v[182:183], v[200:201], off
	global_store_dwordx2 v[182:183], v[204:205], off offset:32
	v_lshl_add_u64 v[182:183], v[182:183], 0, s[8:9]
	s_waitcnt lgkmcnt(0)
	s_barrier
	s_mov_b32 s10, 6
